# strategy 9 serial-chain shortening: NSA top-k threshold search issues both per-step compares back to back (second into an SGPR pair), one VALU->SALU hand-off per step instead of two
# baseline (speedup 1.0000x reference)
; __device__ __forceinline__ void phase_nsa_attn(const Params& p, char* smem, volatile LAS unsigned* vb_) {
;     ...
;             const u32 cand = T | (1u << bit);
;             const int c = __builtin_popcountll(__builtin_amdgcn_ballot_w64(b0 >= cand)) +
;                           __builtin_popcountll(__builtin_amdgcn_ballot_w64(b1 >= cand));
;             if (c >= 13) T = cand;
;           }
.LBB0_120:
	s_or_b64 exec, exec, s[10:11]
	s_brev_b32 s11, -4
	v_cmp_lt_u32_e32 vcc, s11, v2
	v_cmp_lt_u32_e64 s[98:99], s11, v0
	s_bcnt1_i32_b64 s10, vcc
	s_bcnt1_i32_b64 s11, s[98:99]
	s_add_i32 s11, s11, s10
	s_cmp_gt_u32 s11, 12
	s_cselect_b32 s10, 2.0, 0
	s_or_b32 s11, s10, 0x20000000
	v_cmp_le_u32_e32 vcc, s11, v2
	v_cmp_le_u32_e64 s[98:99], s11, v0
	s_bcnt1_i32_b64 s12, vcc
	s_bcnt1_i32_b64 s13, s[98:99]
	s_add_i32 s13, s13, s12
	s_cmp_gt_u32 s13, 12
	s_cselect_b32 s10, s11, s10
	s_or_b32 s11, s10, 0x10000000
	v_cmp_le_u32_e32 vcc, s11, v2
	v_cmp_le_u32_e64 s[98:99], s11, v0
	s_bcnt1_i32_b64 s12, vcc
	s_bcnt1_i32_b64 s13, s[98:99]
	s_add_i32 s13, s13, s12
	s_cmp_gt_u32 s13, 12
	s_cselect_b32 s10, s11, s10
	s_or_b32 s11, s10, 0x8000000
	v_cmp_le_u32_e32 vcc, s11, v2
	v_cmp_le_u32_e64 s[98:99], s11, v0
	s_bcnt1_i32_b64 s12, vcc
	s_bcnt1_i32_b64 s13, s[98:99]
	s_add_i32 s13, s13, s12
	s_cmp_gt_u32 s13, 12
	s_cselect_b32 s10, s11, s10
	s_or_b32 s11, s10, 0x4000000
	v_cmp_le_u32_e32 vcc, s11, v2
	v_cmp_le_u32_e64 s[98:99], s11, v0
	s_bcnt1_i32_b64 s12, vcc
	s_bcnt1_i32_b64 s13, s[98:99]
	s_add_i32 s13, s13, s12
	s_cmp_gt_u32 s13, 12
	s_cselect_b32 s10, s11, s10
	s_or_b32 s11, s10, 0x2000000
	v_cmp_le_u32_e32 vcc, s11, v2
	v_cmp_le_u32_e64 s[98:99], s11, v0
	s_bcnt1_i32_b64 s12, vcc
	s_bcnt1_i32_b64 s13, s[98:99]
	s_add_i32 s13, s13, s12
	s_cmp_gt_u32 s13, 12
	s_cselect_b32 s10, s11, s10
	s_or_b32 s11, s10, 0x1000000
	v_cmp_le_u32_e32 vcc, s11, v2
	v_cmp_le_u32_e64 s[98:99], s11, v0
	s_bcnt1_i32_b64 s12, vcc
	s_bcnt1_i32_b64 s13, s[98:99]
	s_add_i32 s13, s13, s12
	s_cmp_gt_u32 s13, 12
	s_cselect_b32 s10, s11, s10
	s_or_b32 s11, s10, 0x800000
	v_cmp_le_u32_e32 vcc, s11, v2
	v_cmp_le_u32_e64 s[98:99], s11, v0
	s_bcnt1_i32_b64 s12, vcc
	s_bcnt1_i32_b64 s13, s[98:99]
	s_add_i32 s13, s13, s12
	s_cmp_gt_u32 s13, 12
	s_cselect_b32 s10, s11, s10
	s_or_b32 s11, s10, 0x400000
	v_cmp_le_u32_e32 vcc, s11, v2
	v_cmp_le_u32_e64 s[98:99], s11, v0
	s_bcnt1_i32_b64 s12, vcc
	s_bcnt1_i32_b64 s13, s[98:99]
	s_add_i32 s13, s13, s12
	s_cmp_gt_u32 s13, 12
	s_cselect_b32 s10, s11, s10
	s_or_b32 s11, s10, 0x200000
	v_cmp_le_u32_e32 vcc, s11, v2
	v_cmp_le_u32_e64 s[98:99], s11, v0
	s_bcnt1_i32_b64 s12, vcc
	s_bcnt1_i32_b64 s13, s[98:99]
	s_add_i32 s13, s13, s12
	s_cmp_gt_u32 s13, 12
	s_cselect_b32 s10, s11, s10
	s_or_b32 s11, s10, 0x100000
	v_cmp_le_u32_e32 vcc, s11, v2
	v_cmp_le_u32_e64 s[98:99], s11, v0
	s_bcnt1_i32_b64 s12, vcc
	s_bcnt1_i32_b64 s13, s[98:99]
	s_add_i32 s13, s13, s12
	s_cmp_gt_u32 s13, 12
	s_cselect_b32 s10, s11, s10
	s_or_b32 s11, s10, 0x80000
	v_cmp_le_u32_e32 vcc, s11, v2
	v_cmp_le_u32_e64 s[98:99], s11, v0
	s_bcnt1_i32_b64 s12, vcc
	s_bcnt1_i32_b64 s13, s[98:99]
	s_add_i32 s13, s13, s12
	s_cmp_gt_u32 s13, 12
	s_cselect_b32 s10, s11, s10
	s_or_b32 s11, s10, 0x40000
	v_cmp_le_u32_e32 vcc, s11, v2
	v_cmp_le_u32_e64 s[98:99], s11, v0
	s_bcnt1_i32_b64 s12, vcc
	s_bcnt1_i32_b64 s13, s[98:99]
	s_add_i32 s13, s13, s12
	s_cmp_gt_u32 s13, 12
	s_cselect_b32 s10, s11, s10
	s_or_b32 s11, s10, 0x20000
	v_cmp_le_u32_e32 vcc, s11, v2
	v_cmp_le_u32_e64 s[98:99], s11, v0
	s_bcnt1_i32_b64 s12, vcc
	s_bcnt1_i32_b64 s13, s[98:99]
	s_add_i32 s13, s13, s12
	s_cmp_gt_u32 s13, 12
	s_cselect_b32 s10, s11, s10
	s_or_b32 s11, s10, 0x10000
	v_cmp_le_u32_e32 vcc, s11, v2
	v_cmp_le_u32_e64 s[98:99], s11, v0
	s_bcnt1_i32_b64 s12, vcc
	s_bcnt1_i32_b64 s13, s[98:99]
	s_add_i32 s13, s13, s12
	s_cmp_gt_u32 s13, 12
	s_cselect_b32 s10, s11, s10
	s_or_b32 s11, s10, 0x8000
	v_cmp_le_u32_e32 vcc, s11, v2
	v_cmp_le_u32_e64 s[98:99], s11, v0
	s_bcnt1_i32_b64 s12, vcc
	s_bcnt1_i32_b64 s13, s[98:99]
	s_add_i32 s13, s13, s12
	s_cmp_gt_u32 s13, 12
	s_cselect_b32 s10, s11, s10
	s_or_b32 s11, s10, 0x4000
	v_cmp_le_u32_e32 vcc, s11, v2
	v_cmp_le_u32_e64 s[98:99], s11, v0
	s_bcnt1_i32_b64 s12, vcc
; __device__ __forceinline__ void phase_nsa_attn(const Params& p, char* smem, volatile LAS unsigned* vb_) {
;     ...
;             const u32 cand = T | (1u << bit);
;             const int c = __builtin_popcountll(__builtin_amdgcn_ballot_w64(b0 >= cand)) +
;                           __builtin_popcountll(__builtin_amdgcn_ballot_w64(b1 >= cand));
;             if (c >= 13) T = cand;
;           }
;           u64 g0 = __builtin_amdgcn_ballot_w64(b0 > T);
;           u64 g1 = __builtin_amdgcn_ballot_w64(b1 > T);
;           u64 e0 = __builtin_amdgcn_ballot_w64(b0 == T);
;           u64 e1 = __builtin_amdgcn_ballot_w64(b1 == T);
;           int need = 13 - __builtin_popcountll(g0) - __builtin_popcountll(g1);
	s_bcnt1_i32_b64 s13, s[98:99]
	s_add_i32 s13, s13, s12
	s_cmp_gt_u32 s13, 12
	s_cselect_b32 s10, s11, s10
	s_or_b32 s11, s10, 0x2000
	v_cmp_le_u32_e32 vcc, s11, v2
	v_cmp_le_u32_e64 s[98:99], s11, v0
	s_bcnt1_i32_b64 s12, vcc
	s_bcnt1_i32_b64 s13, s[98:99]
	s_add_i32 s13, s13, s12
	s_cmp_gt_u32 s13, 12
	s_cselect_b32 s10, s11, s10
	s_or_b32 s11, s10, 0x1000
	v_cmp_le_u32_e32 vcc, s11, v2
	v_cmp_le_u32_e64 s[98:99], s11, v0
	s_bcnt1_i32_b64 s12, vcc
	s_bcnt1_i32_b64 s13, s[98:99]
	s_add_i32 s13, s13, s12
	s_cmp_gt_u32 s13, 12
	s_cselect_b32 s10, s11, s10
	s_or_b32 s11, s10, 0x800
	v_cmp_le_u32_e32 vcc, s11, v2
	v_cmp_le_u32_e64 s[98:99], s11, v0
	s_bcnt1_i32_b64 s12, vcc
	s_bcnt1_i32_b64 s13, s[98:99]
	s_add_i32 s13, s13, s12
	s_cmp_gt_u32 s13, 12
	s_cselect_b32 s10, s11, s10
	s_or_b32 s11, s10, 0x400
	v_cmp_le_u32_e32 vcc, s11, v2
	v_cmp_le_u32_e64 s[98:99], s11, v0
	s_bcnt1_i32_b64 s12, vcc
	s_bcnt1_i32_b64 s13, s[98:99]
	s_add_i32 s13, s13, s12
	s_cmp_gt_u32 s13, 12
	s_cselect_b32 s10, s11, s10
	s_or_b32 s11, s10, 0x200
	v_cmp_le_u32_e32 vcc, s11, v2
	v_cmp_le_u32_e64 s[98:99], s11, v0
	s_bcnt1_i32_b64 s12, vcc
	s_bcnt1_i32_b64 s13, s[98:99]
	s_add_i32 s13, s13, s12
	s_cmp_gt_u32 s13, 12
	s_cselect_b32 s10, s11, s10
	s_or_b32 s11, s10, 0x100
	v_cmp_le_u32_e32 vcc, s11, v2
	v_cmp_le_u32_e64 s[98:99], s11, v0
	s_bcnt1_i32_b64 s12, vcc
	s_bcnt1_i32_b64 s13, s[98:99]
	s_add_i32 s13, s13, s12
	s_cmp_gt_u32 s13, 12
	s_cselect_b32 s10, s11, s10
	s_or_b32 s11, s10, 0x80
	v_cmp_le_u32_e32 vcc, s11, v2
	v_cmp_le_u32_e64 s[98:99], s11, v0
	s_bcnt1_i32_b64 s12, vcc
	s_bcnt1_i32_b64 s13, s[98:99]
	s_add_i32 s13, s13, s12
	s_cmp_gt_u32 s13, 12
	s_cselect_b32 s10, s11, s10
	s_or_b32 s11, s10, 64
	v_cmp_le_u32_e32 vcc, s11, v2
	v_cmp_le_u32_e64 s[98:99], s11, v0
	s_bcnt1_i32_b64 s12, vcc
	s_bcnt1_i32_b64 s13, s[98:99]
	s_add_i32 s13, s13, s12
	s_cmp_gt_u32 s13, 12
	s_cselect_b32 s10, s11, s10
	s_or_b32 s11, s10, 32
	v_cmp_le_u32_e32 vcc, s11, v2
	v_cmp_le_u32_e64 s[98:99], s11, v0
	s_bcnt1_i32_b64 s12, vcc
	s_bcnt1_i32_b64 s13, s[98:99]
	s_add_i32 s13, s13, s12
	s_cmp_gt_u32 s13, 12
	s_cselect_b32 s10, s11, s10
	s_or_b32 s11, s10, 16
	v_cmp_le_u32_e32 vcc, s11, v2
	v_cmp_le_u32_e64 s[98:99], s11, v0
	s_bcnt1_i32_b64 s12, vcc
	s_bcnt1_i32_b64 s13, s[98:99]
	s_add_i32 s13, s13, s12
	s_cmp_gt_u32 s13, 12
	s_cselect_b32 s10, s11, s10
	s_or_b32 s11, s10, 8
	v_cmp_le_u32_e32 vcc, s11, v2
	v_cmp_le_u32_e64 s[98:99], s11, v0
	s_bcnt1_i32_b64 s12, vcc
	s_bcnt1_i32_b64 s13, s[98:99]
	s_add_i32 s13, s13, s12
	s_cmp_gt_u32 s13, 12
	s_cselect_b32 s10, s11, s10
	s_or_b32 s11, s10, 4
	v_cmp_le_u32_e32 vcc, s11, v2
	v_cmp_le_u32_e64 s[98:99], s11, v0
	s_bcnt1_i32_b64 s12, vcc
	s_bcnt1_i32_b64 s13, s[98:99]
	s_add_i32 s13, s13, s12
	s_cmp_gt_u32 s13, 12
	s_cselect_b32 s10, s11, s10
	s_or_b32 s11, s10, 2
	v_cmp_le_u32_e32 vcc, s11, v2
	v_cmp_le_u32_e64 s[98:99], s11, v0
	s_bcnt1_i32_b64 s12, vcc
	s_bcnt1_i32_b64 s13, s[98:99]
	s_add_i32 s13, s13, s12
	s_cmp_gt_u32 s13, 12
	s_cselect_b32 s10, s11, s10
	s_or_b32 s11, s10, 1
	v_cmp_le_u32_e32 vcc, s11, v2
	v_cmp_le_u32_e64 s[98:99], s11, v0
	s_bcnt1_i32_b64 s12, vcc
	s_bcnt1_i32_b64 s13, s[98:99]
	s_add_i32 s13, s13, s12
	s_cmp_gt_u32 s13, 12
	s_cselect_b32 s10, s11, s10
	v_cmp_lt_u32_e64 s[12:13], s10, v2
	v_cmp_lt_u32_e64 s[90:91], s10, v0
	v_cmp_eq_u32_e64 s[36:37], s10, v2
	v_cmp_eq_u32_e64 s[22:23], s10, v0
	s_bcnt1_i32_b64 s10, s[12:13]
	s_bcnt1_i32_b64 s11, s[90:91]
	s_add_i32 s10, s11, s10
	s_cmp_gt_u32 s10, 12
	s_cselect_b64 s[38:39], -1, 0
	s_or_b64 s[40:41], s[22:23], s[36:37]
	s_cmp_eq_u64 s[40:41], 0
	s_cselect_b64 s[40:41], -1, 0
	s_or_b64 s[38:39], s[38:39], s[40:41]
	s_and_b64 vcc, exec, s[38:39]
	s_cbranch_vccnz .LBB0_128
	s_sub_i32 s40, 13, s10
	s_cmp_eq_u64 s[36:37], 0
	s_cbranch_scc0 .LBB0_125
	s_branch .LBB0_123

; __device__ __forceinline__ void phase_nsa_attn(const Params& p, char* smem, volatile LAS unsigned* vb_) {
;     ...
;             const u32 cand = T | (1u << bit);
;             const int c = __builtin_popcountll(__builtin_amdgcn_ballot_w64(b0 >= cand)) +
;                           __builtin_popcountll(__builtin_amdgcn_ballot_w64(b1 >= cand));
;             if (c >= 13) T = cand;
;           }
.LBB0_132:
	s_or_b64 exec, exec, s[10:11]
	s_brev_b32 s11, -4
	v_cmp_lt_u32_e32 vcc, s11, v2
	v_cmp_lt_u32_e64 s[98:99], s11, v0
	s_bcnt1_i32_b64 s10, vcc
	s_bcnt1_i32_b64 s11, s[98:99]
	s_add_i32 s11, s11, s10
	s_cmp_gt_u32 s11, 12
	s_cselect_b32 s10, 2.0, 0
	s_or_b32 s11, s10, 0x20000000
	v_cmp_le_u32_e32 vcc, s11, v2
	v_cmp_le_u32_e64 s[98:99], s11, v0
	s_bcnt1_i32_b64 s22, vcc
	s_bcnt1_i32_b64 s23, s[98:99]
	s_add_i32 s23, s23, s22
	s_cmp_gt_u32 s23, 12
	s_cselect_b32 s10, s11, s10
	s_or_b32 s11, s10, 0x10000000
	v_cmp_le_u32_e32 vcc, s11, v2
	v_cmp_le_u32_e64 s[98:99], s11, v0
	s_bcnt1_i32_b64 s22, vcc
	s_bcnt1_i32_b64 s23, s[98:99]
	s_add_i32 s23, s23, s22
	s_cmp_gt_u32 s23, 12
	s_cselect_b32 s10, s11, s10
	s_or_b32 s11, s10, 0x8000000
	v_cmp_le_u32_e32 vcc, s11, v2
	v_cmp_le_u32_e64 s[98:99], s11, v0
	s_bcnt1_i32_b64 s22, vcc
	s_bcnt1_i32_b64 s23, s[98:99]
	s_add_i32 s23, s23, s22
	s_cmp_gt_u32 s23, 12
	s_cselect_b32 s10, s11, s10
	s_or_b32 s11, s10, 0x4000000
	v_cmp_le_u32_e32 vcc, s11, v2
	v_cmp_le_u32_e64 s[98:99], s11, v0
	s_bcnt1_i32_b64 s22, vcc
	s_bcnt1_i32_b64 s23, s[98:99]
	s_add_i32 s23, s23, s22
	s_cmp_gt_u32 s23, 12
	s_cselect_b32 s10, s11, s10
	s_or_b32 s11, s10, 0x2000000
	v_cmp_le_u32_e32 vcc, s11, v2
	v_cmp_le_u32_e64 s[98:99], s11, v0
	s_bcnt1_i32_b64 s22, vcc
	s_bcnt1_i32_b64 s23, s[98:99]
	s_add_i32 s23, s23, s22
	s_cmp_gt_u32 s23, 12
	s_cselect_b32 s10, s11, s10
	s_or_b32 s11, s10, 0x1000000
	v_cmp_le_u32_e32 vcc, s11, v2
	v_cmp_le_u32_e64 s[98:99], s11, v0
	s_bcnt1_i32_b64 s22, vcc
	s_bcnt1_i32_b64 s23, s[98:99]
	s_add_i32 s23, s23, s22
	s_cmp_gt_u32 s23, 12
	s_cselect_b32 s10, s11, s10
	s_or_b32 s11, s10, 0x800000
	v_cmp_le_u32_e32 vcc, s11, v2
	v_cmp_le_u32_e64 s[98:99], s11, v0
	s_bcnt1_i32_b64 s22, vcc
	s_bcnt1_i32_b64 s23, s[98:99]
	s_add_i32 s23, s23, s22
	s_cmp_gt_u32 s23, 12
	s_cselect_b32 s10, s11, s10
	s_or_b32 s11, s10, 0x400000
	v_cmp_le_u32_e32 vcc, s11, v2
	v_cmp_le_u32_e64 s[98:99], s11, v0
	s_bcnt1_i32_b64 s22, vcc
	s_bcnt1_i32_b64 s23, s[98:99]
	s_add_i32 s23, s23, s22
	s_cmp_gt_u32 s23, 12
	s_cselect_b32 s10, s11, s10
	s_or_b32 s11, s10, 0x200000
	v_cmp_le_u32_e32 vcc, s11, v2
	v_cmp_le_u32_e64 s[98:99], s11, v0
	s_bcnt1_i32_b64 s22, vcc
	s_bcnt1_i32_b64 s23, s[98:99]
	s_add_i32 s23, s23, s22
	s_cmp_gt_u32 s23, 12
	s_cselect_b32 s10, s11, s10
	s_or_b32 s11, s10, 0x100000
	v_cmp_le_u32_e32 vcc, s11, v2
	v_cmp_le_u32_e64 s[98:99], s11, v0
	s_bcnt1_i32_b64 s22, vcc
	s_bcnt1_i32_b64 s23, s[98:99]
	s_add_i32 s23, s23, s22
	s_cmp_gt_u32 s23, 12
	s_cselect_b32 s10, s11, s10
	s_or_b32 s11, s10, 0x80000
	v_cmp_le_u32_e32 vcc, s11, v2
	v_cmp_le_u32_e64 s[98:99], s11, v0
	s_bcnt1_i32_b64 s22, vcc
	s_bcnt1_i32_b64 s23, s[98:99]
	s_add_i32 s23, s23, s22
	s_cmp_gt_u32 s23, 12
	s_cselect_b32 s10, s11, s10
	s_or_b32 s11, s10, 0x40000
	v_cmp_le_u32_e32 vcc, s11, v2
	v_cmp_le_u32_e64 s[98:99], s11, v0
	s_bcnt1_i32_b64 s22, vcc
	s_bcnt1_i32_b64 s23, s[98:99]
	s_add_i32 s23, s23, s22
	s_cmp_gt_u32 s23, 12
	s_cselect_b32 s10, s11, s10
	s_or_b32 s11, s10, 0x20000
	v_cmp_le_u32_e32 vcc, s11, v2
	v_cmp_le_u32_e64 s[98:99], s11, v0
	s_bcnt1_i32_b64 s22, vcc
	s_bcnt1_i32_b64 s23, s[98:99]
	s_add_i32 s23, s23, s22
	s_cmp_gt_u32 s23, 12
	s_cselect_b32 s10, s11, s10
	s_or_b32 s11, s10, 0x10000
	v_cmp_le_u32_e32 vcc, s11, v2
	v_cmp_le_u32_e64 s[98:99], s11, v0
	s_bcnt1_i32_b64 s22, vcc
	s_bcnt1_i32_b64 s23, s[98:99]
	s_add_i32 s23, s23, s22
	s_cmp_gt_u32 s23, 12
	s_cselect_b32 s10, s11, s10
	s_or_b32 s11, s10, 0x8000
	v_cmp_le_u32_e32 vcc, s11, v2
	v_cmp_le_u32_e64 s[98:99], s11, v0
	s_bcnt1_i32_b64 s22, vcc
	s_bcnt1_i32_b64 s23, s[98:99]
	s_add_i32 s23, s23, s22
	s_cmp_gt_u32 s23, 12
	s_cselect_b32 s10, s11, s10
	s_or_b32 s11, s10, 0x4000
	v_cmp_le_u32_e32 vcc, s11, v2
	v_cmp_le_u32_e64 s[98:99], s11, v0
	s_bcnt1_i32_b64 s22, vcc
; __device__ __forceinline__ void phase_nsa_attn(const Params& p, char* smem, volatile LAS unsigned* vb_) {
;     ...
;             const u32 cand = T | (1u << bit);
;             const int c = __builtin_popcountll(__builtin_amdgcn_ballot_w64(b0 >= cand)) +
;                           __builtin_popcountll(__builtin_amdgcn_ballot_w64(b1 >= cand));
;             if (c >= 13) T = cand;
;           }
;           u64 g0 = __builtin_amdgcn_ballot_w64(b0 > T);
;           u64 g1 = __builtin_amdgcn_ballot_w64(b1 > T);
;           u64 e0 = __builtin_amdgcn_ballot_w64(b0 == T);
;           u64 e1 = __builtin_amdgcn_ballot_w64(b1 == T);
;           int need = 13 - __builtin_popcountll(g0) - __builtin_popcountll(g1);
	s_bcnt1_i32_b64 s23, s[98:99]
	s_add_i32 s23, s23, s22
	s_cmp_gt_u32 s23, 12
	s_cselect_b32 s10, s11, s10
	s_or_b32 s11, s10, 0x2000
	v_cmp_le_u32_e32 vcc, s11, v2
	v_cmp_le_u32_e64 s[98:99], s11, v0
	s_bcnt1_i32_b64 s22, vcc
	s_bcnt1_i32_b64 s23, s[98:99]
	s_add_i32 s23, s23, s22
	s_cmp_gt_u32 s23, 12
	s_cselect_b32 s10, s11, s10
	s_or_b32 s11, s10, 0x1000
	v_cmp_le_u32_e32 vcc, s11, v2
	v_cmp_le_u32_e64 s[98:99], s11, v0
	s_bcnt1_i32_b64 s22, vcc
	s_bcnt1_i32_b64 s23, s[98:99]
	s_add_i32 s23, s23, s22
	s_cmp_gt_u32 s23, 12
	s_cselect_b32 s10, s11, s10
	s_or_b32 s11, s10, 0x800
	v_cmp_le_u32_e32 vcc, s11, v2
	v_cmp_le_u32_e64 s[98:99], s11, v0
	s_bcnt1_i32_b64 s22, vcc
	s_bcnt1_i32_b64 s23, s[98:99]
	s_add_i32 s23, s23, s22
	s_cmp_gt_u32 s23, 12
	s_cselect_b32 s10, s11, s10
	s_or_b32 s11, s10, 0x400
	v_cmp_le_u32_e32 vcc, s11, v2
	v_cmp_le_u32_e64 s[98:99], s11, v0
	s_bcnt1_i32_b64 s22, vcc
	s_bcnt1_i32_b64 s23, s[98:99]
	s_add_i32 s23, s23, s22
	s_cmp_gt_u32 s23, 12
	s_cselect_b32 s10, s11, s10
	s_or_b32 s11, s10, 0x200
	v_cmp_le_u32_e32 vcc, s11, v2
	v_cmp_le_u32_e64 s[98:99], s11, v0
	s_bcnt1_i32_b64 s22, vcc
	s_bcnt1_i32_b64 s23, s[98:99]
	s_add_i32 s23, s23, s22
	s_cmp_gt_u32 s23, 12
	s_cselect_b32 s10, s11, s10
	s_or_b32 s11, s10, 0x100
	v_cmp_le_u32_e32 vcc, s11, v2
	v_cmp_le_u32_e64 s[98:99], s11, v0
	s_bcnt1_i32_b64 s22, vcc
	s_bcnt1_i32_b64 s23, s[98:99]
	s_add_i32 s23, s23, s22
	s_cmp_gt_u32 s23, 12
	s_cselect_b32 s10, s11, s10
	s_or_b32 s11, s10, 0x80
	v_cmp_le_u32_e32 vcc, s11, v2
	v_cmp_le_u32_e64 s[98:99], s11, v0
	s_bcnt1_i32_b64 s22, vcc
	s_bcnt1_i32_b64 s23, s[98:99]
	s_add_i32 s23, s23, s22
	s_cmp_gt_u32 s23, 12
	s_cselect_b32 s10, s11, s10
	s_or_b32 s11, s10, 64
	v_cmp_le_u32_e32 vcc, s11, v2
	v_cmp_le_u32_e64 s[98:99], s11, v0
	s_bcnt1_i32_b64 s22, vcc
	s_bcnt1_i32_b64 s23, s[98:99]
	s_add_i32 s23, s23, s22
	s_cmp_gt_u32 s23, 12
	s_cselect_b32 s10, s11, s10
	s_or_b32 s11, s10, 32
	v_cmp_le_u32_e32 vcc, s11, v2
	v_cmp_le_u32_e64 s[98:99], s11, v0
	s_bcnt1_i32_b64 s22, vcc
	s_bcnt1_i32_b64 s23, s[98:99]
	s_add_i32 s23, s23, s22
	s_cmp_gt_u32 s23, 12
	s_cselect_b32 s10, s11, s10
	s_or_b32 s11, s10, 16
	v_cmp_le_u32_e32 vcc, s11, v2
	v_cmp_le_u32_e64 s[98:99], s11, v0
	s_bcnt1_i32_b64 s22, vcc
	s_bcnt1_i32_b64 s23, s[98:99]
	s_add_i32 s23, s23, s22
	s_cmp_gt_u32 s23, 12
	s_cselect_b32 s10, s11, s10
	s_or_b32 s11, s10, 8
	v_cmp_le_u32_e32 vcc, s11, v2
	v_cmp_le_u32_e64 s[98:99], s11, v0
	s_bcnt1_i32_b64 s22, vcc
	s_bcnt1_i32_b64 s23, s[98:99]
	s_add_i32 s23, s23, s22
	s_cmp_gt_u32 s23, 12
	s_cselect_b32 s10, s11, s10
	s_or_b32 s11, s10, 4
	v_cmp_le_u32_e32 vcc, s11, v2
	v_cmp_le_u32_e64 s[98:99], s11, v0
	s_bcnt1_i32_b64 s22, vcc
	s_bcnt1_i32_b64 s23, s[98:99]
	s_add_i32 s23, s23, s22
	s_cmp_gt_u32 s23, 12
	s_cselect_b32 s10, s11, s10
	s_or_b32 s11, s10, 2
	v_cmp_le_u32_e32 vcc, s11, v2
	v_cmp_le_u32_e64 s[98:99], s11, v0
	s_bcnt1_i32_b64 s22, vcc
	s_bcnt1_i32_b64 s23, s[98:99]
	s_add_i32 s23, s23, s22
	s_cmp_gt_u32 s23, 12
	s_cselect_b32 s10, s11, s10
	s_or_b32 s11, s10, 1
	v_cmp_le_u32_e32 vcc, s11, v2
	v_cmp_le_u32_e64 s[98:99], s11, v0
	s_bcnt1_i32_b64 s22, vcc
	s_bcnt1_i32_b64 s23, s[98:99]
	s_add_i32 s23, s23, s22
	s_cmp_gt_u32 s23, 12
	s_cselect_b32 s10, s11, s10
	v_cmp_lt_u32_e64 s[38:39], s10, v2
	v_cmp_lt_u32_e64 s[22:23], s10, v0
	v_cmp_eq_u32_e64 s[40:41], s10, v2
	v_cmp_eq_u32_e64 s[36:37], s10, v0
	s_bcnt1_i32_b64 s10, s[38:39]
	s_bcnt1_i32_b64 s11, s[22:23]
	s_add_i32 s10, s11, s10
	s_cmp_gt_u32 s10, 12
	s_cselect_b64 s[62:63], -1, 0
	s_or_b64 s[64:65], s[36:37], s[40:41]
	s_cmp_eq_u64 s[64:65], 0
	s_cselect_b64 s[64:65], -1, 0
	s_or_b64 s[62:63], s[62:63], s[64:65]
	s_and_b64 vcc, exec, s[62:63]
	s_cbranch_vccnz .LBB0_140
	s_sub_i32 s58, 13, s10
	s_cmp_eq_u64 s[40:41], 0
	s_cbranch_scc0 .LBB0_137
	s_branch .LBB0_135

; __device__ __forceinline__ void phase_nsa_attn(const Params& p, char* smem, volatile LAS unsigned* vb_) {
;     ...
;             const u32 cand = T | (1u << bit);
;             const int c = __builtin_popcountll(__builtin_amdgcn_ballot_w64(b0 >= cand)) +
;                           __builtin_popcountll(__builtin_amdgcn_ballot_w64(b1 >= cand));
;             if (c >= 13) T = cand;
;           }
.LBB0_144:
	s_or_b64 exec, exec, s[10:11]
	s_brev_b32 s11, -4
	v_cmp_lt_u32_e32 vcc, s11, v2
	v_cmp_lt_u32_e64 s[98:99], s11, v0
	s_bcnt1_i32_b64 s10, vcc
	s_bcnt1_i32_b64 s11, s[98:99]
	s_add_i32 s11, s11, s10
	s_cmp_gt_u32 s11, 12
	s_cselect_b32 s10, 2.0, 0
	s_or_b32 s11, s10, 0x20000000
	v_cmp_le_u32_e32 vcc, s11, v2
	v_cmp_le_u32_e64 s[98:99], s11, v0
	s_bcnt1_i32_b64 s36, vcc
	s_bcnt1_i32_b64 s37, s[98:99]
	s_add_i32 s37, s37, s36
	s_cmp_gt_u32 s37, 12
	s_cselect_b32 s10, s11, s10
	s_or_b32 s11, s10, 0x10000000
	v_cmp_le_u32_e32 vcc, s11, v2
	v_cmp_le_u32_e64 s[98:99], s11, v0
	s_bcnt1_i32_b64 s36, vcc
	s_bcnt1_i32_b64 s37, s[98:99]
	s_add_i32 s37, s37, s36
	s_cmp_gt_u32 s37, 12
	s_cselect_b32 s10, s11, s10
	s_or_b32 s11, s10, 0x8000000
	v_cmp_le_u32_e32 vcc, s11, v2
	v_cmp_le_u32_e64 s[98:99], s11, v0
	s_bcnt1_i32_b64 s36, vcc
	s_bcnt1_i32_b64 s37, s[98:99]
	s_add_i32 s37, s37, s36
	s_cmp_gt_u32 s37, 12
	s_cselect_b32 s10, s11, s10
	s_or_b32 s11, s10, 0x4000000
	v_cmp_le_u32_e32 vcc, s11, v2
	v_cmp_le_u32_e64 s[98:99], s11, v0
	s_bcnt1_i32_b64 s36, vcc
	s_bcnt1_i32_b64 s37, s[98:99]
	s_add_i32 s37, s37, s36
	s_cmp_gt_u32 s37, 12
	s_cselect_b32 s10, s11, s10
	s_or_b32 s11, s10, 0x2000000
	v_cmp_le_u32_e32 vcc, s11, v2
	v_cmp_le_u32_e64 s[98:99], s11, v0
	s_bcnt1_i32_b64 s36, vcc
	s_bcnt1_i32_b64 s37, s[98:99]
	s_add_i32 s37, s37, s36
	s_cmp_gt_u32 s37, 12
	s_cselect_b32 s10, s11, s10
	s_or_b32 s11, s10, 0x1000000
	v_cmp_le_u32_e32 vcc, s11, v2
	v_cmp_le_u32_e64 s[98:99], s11, v0
	s_bcnt1_i32_b64 s36, vcc
	s_bcnt1_i32_b64 s37, s[98:99]
	s_add_i32 s37, s37, s36
	s_cmp_gt_u32 s37, 12
	s_cselect_b32 s10, s11, s10
	s_or_b32 s11, s10, 0x800000
	v_cmp_le_u32_e32 vcc, s11, v2
	v_cmp_le_u32_e64 s[98:99], s11, v0
	s_bcnt1_i32_b64 s36, vcc
	s_bcnt1_i32_b64 s37, s[98:99]
	s_add_i32 s37, s37, s36
	s_cmp_gt_u32 s37, 12
	s_cselect_b32 s10, s11, s10
	s_or_b32 s11, s10, 0x400000
	v_cmp_le_u32_e32 vcc, s11, v2
	v_cmp_le_u32_e64 s[98:99], s11, v0
	s_bcnt1_i32_b64 s36, vcc
	s_bcnt1_i32_b64 s37, s[98:99]
	s_add_i32 s37, s37, s36
	s_cmp_gt_u32 s37, 12
	s_cselect_b32 s10, s11, s10
	s_or_b32 s11, s10, 0x200000
	v_cmp_le_u32_e32 vcc, s11, v2
	v_cmp_le_u32_e64 s[98:99], s11, v0
	s_bcnt1_i32_b64 s36, vcc
	s_bcnt1_i32_b64 s37, s[98:99]
	s_add_i32 s37, s37, s36
	s_cmp_gt_u32 s37, 12
	s_cselect_b32 s10, s11, s10
	s_or_b32 s11, s10, 0x100000
	v_cmp_le_u32_e32 vcc, s11, v2
	v_cmp_le_u32_e64 s[98:99], s11, v0
	s_bcnt1_i32_b64 s36, vcc
	s_bcnt1_i32_b64 s37, s[98:99]
	s_add_i32 s37, s37, s36
	s_cmp_gt_u32 s37, 12
	s_cselect_b32 s10, s11, s10
	s_or_b32 s11, s10, 0x80000
	v_cmp_le_u32_e32 vcc, s11, v2
	v_cmp_le_u32_e64 s[98:99], s11, v0
	s_bcnt1_i32_b64 s36, vcc
	s_bcnt1_i32_b64 s37, s[98:99]
	s_add_i32 s37, s37, s36
	s_cmp_gt_u32 s37, 12
	s_cselect_b32 s10, s11, s10
	s_or_b32 s11, s10, 0x40000
	v_cmp_le_u32_e32 vcc, s11, v2
	v_cmp_le_u32_e64 s[98:99], s11, v0
	s_bcnt1_i32_b64 s36, vcc
	s_bcnt1_i32_b64 s37, s[98:99]
	s_add_i32 s37, s37, s36
	s_cmp_gt_u32 s37, 12
	s_cselect_b32 s10, s11, s10
	s_or_b32 s11, s10, 0x20000
	v_cmp_le_u32_e32 vcc, s11, v2
	v_cmp_le_u32_e64 s[98:99], s11, v0
	s_bcnt1_i32_b64 s36, vcc
	s_bcnt1_i32_b64 s37, s[98:99]
	s_add_i32 s37, s37, s36
	s_cmp_gt_u32 s37, 12
	s_cselect_b32 s10, s11, s10
	s_or_b32 s11, s10, 0x10000
	v_cmp_le_u32_e32 vcc, s11, v2
	v_cmp_le_u32_e64 s[98:99], s11, v0
	s_bcnt1_i32_b64 s36, vcc
	s_bcnt1_i32_b64 s37, s[98:99]
	s_add_i32 s37, s37, s36
	s_cmp_gt_u32 s37, 12
	s_cselect_b32 s10, s11, s10
	s_or_b32 s11, s10, 0x8000
	v_cmp_le_u32_e32 vcc, s11, v2
	v_cmp_le_u32_e64 s[98:99], s11, v0
	s_bcnt1_i32_b64 s36, vcc
	s_bcnt1_i32_b64 s37, s[98:99]
	s_add_i32 s37, s37, s36
	s_cmp_gt_u32 s37, 12
	s_cselect_b32 s10, s11, s10
	s_or_b32 s11, s10, 0x4000
	v_cmp_le_u32_e32 vcc, s11, v2
	v_cmp_le_u32_e64 s[98:99], s11, v0
	s_bcnt1_i32_b64 s36, vcc
; __device__ __forceinline__ void phase_nsa_attn(const Params& p, char* smem, volatile LAS unsigned* vb_) {
;     ...
;             const u32 cand = T | (1u << bit);
;             const int c = __builtin_popcountll(__builtin_amdgcn_ballot_w64(b0 >= cand)) +
;                           __builtin_popcountll(__builtin_amdgcn_ballot_w64(b1 >= cand));
;             if (c >= 13) T = cand;
;           }
;           u64 g0 = __builtin_amdgcn_ballot_w64(b0 > T);
;           u64 g1 = __builtin_amdgcn_ballot_w64(b1 > T);
;           u64 e0 = __builtin_amdgcn_ballot_w64(b0 == T);
;           u64 e1 = __builtin_amdgcn_ballot_w64(b1 == T);
;           int need = 13 - __builtin_popcountll(g0) - __builtin_popcountll(g1);
;           while (need > 0 && (e0 | e1)) {
;             if (e0) { const u64 low = e0 & (~e0 + 1ull); g0 |= low; e0 ^= low; }
;             else { const u64 low = e1 & (~e1 + 1ull); g1 |= low; e1 ^= low; }
;     ...
;           }
	s_bcnt1_i32_b64 s37, s[98:99]
	s_add_i32 s37, s37, s36
	s_cmp_gt_u32 s37, 12
	s_cselect_b32 s10, s11, s10
	s_or_b32 s11, s10, 0x2000
	v_cmp_le_u32_e32 vcc, s11, v2
	v_cmp_le_u32_e64 s[98:99], s11, v0
	s_bcnt1_i32_b64 s36, vcc
	s_bcnt1_i32_b64 s37, s[98:99]
	s_add_i32 s37, s37, s36
	s_cmp_gt_u32 s37, 12
	s_cselect_b32 s10, s11, s10
	s_or_b32 s11, s10, 0x1000
	v_cmp_le_u32_e32 vcc, s11, v2
	v_cmp_le_u32_e64 s[98:99], s11, v0
	s_bcnt1_i32_b64 s36, vcc
	s_bcnt1_i32_b64 s37, s[98:99]
	s_add_i32 s37, s37, s36
	s_cmp_gt_u32 s37, 12
	s_cselect_b32 s10, s11, s10
	s_or_b32 s11, s10, 0x800
	v_cmp_le_u32_e32 vcc, s11, v2
	v_cmp_le_u32_e64 s[98:99], s11, v0
	s_bcnt1_i32_b64 s36, vcc
	s_bcnt1_i32_b64 s37, s[98:99]
	s_add_i32 s37, s37, s36
	s_cmp_gt_u32 s37, 12
	s_cselect_b32 s10, s11, s10
	s_or_b32 s11, s10, 0x400
	v_cmp_le_u32_e32 vcc, s11, v2
	v_cmp_le_u32_e64 s[98:99], s11, v0
	s_bcnt1_i32_b64 s36, vcc
	s_bcnt1_i32_b64 s37, s[98:99]
	s_add_i32 s37, s37, s36
	s_cmp_gt_u32 s37, 12
	s_cselect_b32 s10, s11, s10
	s_or_b32 s11, s10, 0x200
	v_cmp_le_u32_e32 vcc, s11, v2
	v_cmp_le_u32_e64 s[98:99], s11, v0
	s_bcnt1_i32_b64 s36, vcc
	s_bcnt1_i32_b64 s37, s[98:99]
	s_add_i32 s37, s37, s36
	s_cmp_gt_u32 s37, 12
	s_cselect_b32 s10, s11, s10
	s_or_b32 s11, s10, 0x100
	v_cmp_le_u32_e32 vcc, s11, v2
	v_cmp_le_u32_e64 s[98:99], s11, v0
	s_bcnt1_i32_b64 s36, vcc
	s_bcnt1_i32_b64 s37, s[98:99]
	s_add_i32 s37, s37, s36
	s_cmp_gt_u32 s37, 12
	s_cselect_b32 s10, s11, s10
	s_or_b32 s11, s10, 0x80
	v_cmp_le_u32_e32 vcc, s11, v2
	v_cmp_le_u32_e64 s[98:99], s11, v0
	s_bcnt1_i32_b64 s36, vcc
	s_bcnt1_i32_b64 s37, s[98:99]
	s_add_i32 s37, s37, s36
	s_cmp_gt_u32 s37, 12
	s_cselect_b32 s10, s11, s10
	s_or_b32 s11, s10, 64
	v_cmp_le_u32_e32 vcc, s11, v2
	v_cmp_le_u32_e64 s[98:99], s11, v0
	s_bcnt1_i32_b64 s36, vcc
	s_bcnt1_i32_b64 s37, s[98:99]
	s_add_i32 s37, s37, s36
	s_cmp_gt_u32 s37, 12
	s_cselect_b32 s10, s11, s10
	s_or_b32 s11, s10, 32
	v_cmp_le_u32_e32 vcc, s11, v2
	v_cmp_le_u32_e64 s[98:99], s11, v0
	s_bcnt1_i32_b64 s36, vcc
	s_bcnt1_i32_b64 s37, s[98:99]
	s_add_i32 s37, s37, s36
	s_cmp_gt_u32 s37, 12
	s_cselect_b32 s10, s11, s10
	s_or_b32 s11, s10, 16
	v_cmp_le_u32_e32 vcc, s11, v2
	v_cmp_le_u32_e64 s[98:99], s11, v0
	s_bcnt1_i32_b64 s36, vcc
	s_bcnt1_i32_b64 s37, s[98:99]
	s_add_i32 s37, s37, s36
	s_cmp_gt_u32 s37, 12
	s_cselect_b32 s10, s11, s10
	s_or_b32 s11, s10, 8
	v_cmp_le_u32_e32 vcc, s11, v2
	v_cmp_le_u32_e64 s[98:99], s11, v0
	s_bcnt1_i32_b64 s36, vcc
	s_bcnt1_i32_b64 s37, s[98:99]
	s_add_i32 s37, s37, s36
	s_cmp_gt_u32 s37, 12
	s_cselect_b32 s10, s11, s10
	s_or_b32 s11, s10, 4
	v_cmp_le_u32_e32 vcc, s11, v2
	v_cmp_le_u32_e64 s[98:99], s11, v0
	s_bcnt1_i32_b64 s36, vcc
	s_bcnt1_i32_b64 s37, s[98:99]
	s_add_i32 s37, s37, s36
	s_cmp_gt_u32 s37, 12
	s_cselect_b32 s10, s11, s10
	s_or_b32 s11, s10, 2
	v_cmp_le_u32_e32 vcc, s11, v2
	v_cmp_le_u32_e64 s[98:99], s11, v0
	s_bcnt1_i32_b64 s36, vcc
	s_bcnt1_i32_b64 s37, s[98:99]
	s_add_i32 s37, s37, s36
	s_cmp_gt_u32 s37, 12
	s_cselect_b32 s10, s11, s10
	s_or_b32 s11, s10, 1
	v_cmp_le_u32_e32 vcc, s11, v2
	v_cmp_le_u32_e64 s[98:99], s11, v0
	s_bcnt1_i32_b64 s36, vcc
	s_bcnt1_i32_b64 s37, s[98:99]
	s_add_i32 s37, s37, s36
	s_cmp_gt_u32 s37, 12
	s_cselect_b32 s10, s11, s10
	v_cmp_lt_u32_e64 s[96:97], s10, v2
	v_cmp_lt_u32_e64 s[40:41], s10, v0
	v_cmp_eq_u32_e64 s[78:79], s10, v2
	v_cmp_eq_u32_e64 s[36:37], s10, v0
	s_bcnt1_i32_b64 s10, s[96:97]
	s_bcnt1_i32_b64 s11, s[40:41]
	s_add_i32 s10, s11, s10
	s_cmp_gt_u32 s10, 12
	s_cselect_b64 s[62:63], -1, 0
	s_or_b64 s[64:65], s[36:37], s[78:79]
	s_cmp_eq_u64 s[64:65], 0
	s_cselect_b64 s[64:65], -1, 0
	s_or_b64 s[62:63], s[62:63], s[64:65]
	s_and_b64 vcc, exec, s[62:63]
	s_cbranch_vccnz .LBB0_152
	s_sub_i32 s58, 13, s10
	s_cmp_eq_u64 s[78:79], 0
	s_cbranch_scc0 .LBB0_149
	s_branch .LBB0_147

; __device__ __forceinline__ void phase_nsa_attn(const Params& p, char* smem, volatile LAS unsigned* vb_) {
;     ...
;           const float* ir = impl + tk * 128;
;           const u32 b0 = (lane >= 1 && lane <= ncand) ? (__float_as_uint(ir[lane]) + 1u) : 0u;
;           const u32 b1 = (lane + 64 <= ncand) ? (__float_as_uint(ir[lane + 64]) + 1u) : 0u;
;           u32 T = 0u;
;     ...
;             const u32 cand = T | (1u << bit);
;             const int c = __builtin_popcountll(__builtin_amdgcn_ballot_w64(b0 >= cand)) +
;                           __builtin_popcountll(__builtin_amdgcn_ballot_w64(b1 >= cand));
;             if (c >= 13) T = cand;
.LBB0_156:
	s_or_b64 exec, exec, s[10:11]
	s_brev_b32 s11, -4
	v_cmp_lt_u32_e32 vcc, s11, v2
	v_cmp_lt_u32_e64 s[98:99], s11, v0
	s_bcnt1_i32_b64 s10, vcc
	s_bcnt1_i32_b64 s11, s[98:99]
	s_add_i32 s11, s11, s10
	s_cmp_gt_u32 s11, 12
	s_cselect_b32 s10, 2.0, 0
	s_or_b32 s11, s10, 0x20000000
	v_cmp_le_u32_e32 vcc, s11, v2
	v_cmp_le_u32_e64 s[98:99], s11, v0
	s_bcnt1_i32_b64 s20, vcc
	s_bcnt1_i32_b64 s21, s[98:99]
	s_add_i32 s21, s21, s20
	s_cmp_gt_u32 s21, 12
	s_cselect_b32 s10, s11, s10
	s_or_b32 s11, s10, 0x10000000
	v_cmp_le_u32_e32 vcc, s11, v2
	v_cmp_le_u32_e64 s[98:99], s11, v0
	s_bcnt1_i32_b64 s20, vcc
	s_bcnt1_i32_b64 s21, s[98:99]
	s_add_i32 s21, s21, s20
	s_cmp_gt_u32 s21, 12
	s_cselect_b32 s10, s11, s10
	s_or_b32 s11, s10, 0x8000000
	v_cmp_le_u32_e32 vcc, s11, v2
	v_cmp_le_u32_e64 s[98:99], s11, v0
	s_bcnt1_i32_b64 s20, vcc
	s_bcnt1_i32_b64 s21, s[98:99]
	s_add_i32 s21, s21, s20
	s_cmp_gt_u32 s21, 12
	s_cselect_b32 s10, s11, s10
	s_or_b32 s11, s10, 0x4000000
	v_cmp_le_u32_e32 vcc, s11, v2
	v_cmp_le_u32_e64 s[98:99], s11, v0
	s_bcnt1_i32_b64 s20, vcc
	s_bcnt1_i32_b64 s21, s[98:99]
	s_add_i32 s21, s21, s20
	s_cmp_gt_u32 s21, 12
	s_cselect_b32 s10, s11, s10
	s_or_b32 s11, s10, 0x2000000
	v_cmp_le_u32_e32 vcc, s11, v2
	v_cmp_le_u32_e64 s[98:99], s11, v0
	s_bcnt1_i32_b64 s20, vcc
	s_bcnt1_i32_b64 s21, s[98:99]
	s_add_i32 s21, s21, s20
	s_cmp_gt_u32 s21, 12
	s_cselect_b32 s10, s11, s10
	s_or_b32 s11, s10, 0x1000000
	v_cmp_le_u32_e32 vcc, s11, v2
	v_cmp_le_u32_e64 s[98:99], s11, v0
	s_bcnt1_i32_b64 s20, vcc
	s_bcnt1_i32_b64 s21, s[98:99]
	s_add_i32 s21, s21, s20
	s_cmp_gt_u32 s21, 12
	s_cselect_b32 s10, s11, s10
	s_or_b32 s11, s10, 0x800000
	v_cmp_le_u32_e32 vcc, s11, v2
	v_cmp_le_u32_e64 s[98:99], s11, v0
	s_bcnt1_i32_b64 s20, vcc
	s_bcnt1_i32_b64 s21, s[98:99]
	s_add_i32 s21, s21, s20
	s_cmp_gt_u32 s21, 12
	s_cselect_b32 s10, s11, s10
	s_or_b32 s11, s10, 0x400000
	v_cmp_le_u32_e32 vcc, s11, v2
	v_cmp_le_u32_e64 s[98:99], s11, v0
	s_bcnt1_i32_b64 s20, vcc
	s_bcnt1_i32_b64 s21, s[98:99]
	s_add_i32 s21, s21, s20
	s_cmp_gt_u32 s21, 12
	s_cselect_b32 s10, s11, s10
	s_or_b32 s11, s10, 0x200000
	v_cmp_le_u32_e32 vcc, s11, v2
	v_cmp_le_u32_e64 s[98:99], s11, v0
	s_bcnt1_i32_b64 s20, vcc
	s_bcnt1_i32_b64 s21, s[98:99]
	s_add_i32 s21, s21, s20
	s_cmp_gt_u32 s21, 12
	s_cselect_b32 s10, s11, s10
	s_or_b32 s11, s10, 0x100000
	v_cmp_le_u32_e32 vcc, s11, v2
	v_cmp_le_u32_e64 s[98:99], s11, v0
	s_bcnt1_i32_b64 s20, vcc
	s_bcnt1_i32_b64 s21, s[98:99]
	s_add_i32 s21, s21, s20
	s_cmp_gt_u32 s21, 12
	s_cselect_b32 s10, s11, s10
	s_or_b32 s11, s10, 0x80000
	v_cmp_le_u32_e32 vcc, s11, v2
	v_cmp_le_u32_e64 s[98:99], s11, v0
	s_bcnt1_i32_b64 s20, vcc
	s_bcnt1_i32_b64 s21, s[98:99]
	s_add_i32 s21, s21, s20
	s_cmp_gt_u32 s21, 12
	s_cselect_b32 s10, s11, s10
	s_or_b32 s11, s10, 0x40000
	v_cmp_le_u32_e32 vcc, s11, v2
	v_cmp_le_u32_e64 s[98:99], s11, v0
	s_bcnt1_i32_b64 s20, vcc
	s_bcnt1_i32_b64 s21, s[98:99]
	s_add_i32 s21, s21, s20
	s_cmp_gt_u32 s21, 12
	s_cselect_b32 s10, s11, s10
	s_or_b32 s11, s10, 0x20000
	v_cmp_le_u32_e32 vcc, s11, v2
	v_cmp_le_u32_e64 s[98:99], s11, v0
	s_bcnt1_i32_b64 s20, vcc
	s_bcnt1_i32_b64 s21, s[98:99]
	s_add_i32 s21, s21, s20
	s_cmp_gt_u32 s21, 12
	s_cselect_b32 s10, s11, s10
	s_or_b32 s11, s10, 0x10000
	v_cmp_le_u32_e32 vcc, s11, v2
	v_cmp_le_u32_e64 s[98:99], s11, v0
	s_bcnt1_i32_b64 s20, vcc
	s_bcnt1_i32_b64 s21, s[98:99]
	s_add_i32 s21, s21, s20
	s_cmp_gt_u32 s21, 12
	s_cselect_b32 s10, s11, s10
	s_or_b32 s11, s10, 0x8000
	v_cmp_le_u32_e32 vcc, s11, v2
	v_cmp_le_u32_e64 s[98:99], s11, v0
	s_bcnt1_i32_b64 s20, vcc
	s_bcnt1_i32_b64 s21, s[98:99]
	s_add_i32 s21, s21, s20
	s_cmp_gt_u32 s21, 12
	s_cselect_b32 s10, s11, s10
	s_or_b32 s11, s10, 0x4000
	v_cmp_le_u32_e32 vcc, s11, v2
	v_cmp_le_u32_e64 s[98:99], s11, v0
	s_bcnt1_i32_b64 s20, vcc
; __device__ __forceinline__ void phase_nsa_attn(const Params& p, char* smem, volatile LAS unsigned* vb_) {
;     ...
;             const u32 cand = T | (1u << bit);
;             const int c = __builtin_popcountll(__builtin_amdgcn_ballot_w64(b0 >= cand)) +
;                           __builtin_popcountll(__builtin_amdgcn_ballot_w64(b1 >= cand));
;             if (c >= 13) T = cand;
;           }
;           u64 g0 = __builtin_amdgcn_ballot_w64(b0 > T);
;           u64 g1 = __builtin_amdgcn_ballot_w64(b1 > T);
;           u64 e0 = __builtin_amdgcn_ballot_w64(b0 == T);
;           u64 e1 = __builtin_amdgcn_ballot_w64(b1 == T);
;           int need = 13 - __builtin_popcountll(g0) - __builtin_popcountll(g1);
;           while (need > 0 && (e0 | e1)) {
;             if (e0) { const u64 low = e0 & (~e0 + 1ull); g0 |= low; e0 ^= low; }
;             else { const u64 low = e1 & (~e1 + 1ull); g1 |= low; e1 ^= low; }
;     ...
;           }
	s_bcnt1_i32_b64 s21, s[98:99]
	s_add_i32 s21, s21, s20
	s_cmp_gt_u32 s21, 12
	s_cselect_b32 s10, s11, s10
	s_or_b32 s11, s10, 0x2000
	v_cmp_le_u32_e32 vcc, s11, v2
	v_cmp_le_u32_e64 s[98:99], s11, v0
	s_bcnt1_i32_b64 s20, vcc
	s_bcnt1_i32_b64 s21, s[98:99]
	s_add_i32 s21, s21, s20
	s_cmp_gt_u32 s21, 12
	s_cselect_b32 s10, s11, s10
	s_or_b32 s11, s10, 0x1000
	v_cmp_le_u32_e32 vcc, s11, v2
	v_cmp_le_u32_e64 s[98:99], s11, v0
	s_bcnt1_i32_b64 s20, vcc
	s_bcnt1_i32_b64 s21, s[98:99]
	s_add_i32 s21, s21, s20
	s_cmp_gt_u32 s21, 12
	s_cselect_b32 s10, s11, s10
	s_or_b32 s11, s10, 0x800
	v_cmp_le_u32_e32 vcc, s11, v2
	v_cmp_le_u32_e64 s[98:99], s11, v0
	s_bcnt1_i32_b64 s20, vcc
	s_bcnt1_i32_b64 s21, s[98:99]
	s_add_i32 s21, s21, s20
	s_cmp_gt_u32 s21, 12
	s_cselect_b32 s10, s11, s10
	s_or_b32 s11, s10, 0x400
	v_cmp_le_u32_e32 vcc, s11, v2
	v_cmp_le_u32_e64 s[98:99], s11, v0
	s_bcnt1_i32_b64 s20, vcc
	s_bcnt1_i32_b64 s21, s[98:99]
	s_add_i32 s21, s21, s20
	s_cmp_gt_u32 s21, 12
	s_cselect_b32 s10, s11, s10
	s_or_b32 s11, s10, 0x200
	v_cmp_le_u32_e32 vcc, s11, v2
	v_cmp_le_u32_e64 s[98:99], s11, v0
	s_bcnt1_i32_b64 s20, vcc
	s_bcnt1_i32_b64 s21, s[98:99]
	s_add_i32 s21, s21, s20
	s_cmp_gt_u32 s21, 12
	s_cselect_b32 s10, s11, s10
	s_or_b32 s11, s10, 0x100
	v_cmp_le_u32_e32 vcc, s11, v2
	v_cmp_le_u32_e64 s[98:99], s11, v0
	s_bcnt1_i32_b64 s20, vcc
	s_bcnt1_i32_b64 s21, s[98:99]
	s_add_i32 s21, s21, s20
	s_cmp_gt_u32 s21, 12
	s_cselect_b32 s10, s11, s10
	s_or_b32 s11, s10, 0x80
	v_cmp_le_u32_e32 vcc, s11, v2
	v_cmp_le_u32_e64 s[98:99], s11, v0
	s_bcnt1_i32_b64 s20, vcc
	s_bcnt1_i32_b64 s21, s[98:99]
	s_add_i32 s21, s21, s20
	s_cmp_gt_u32 s21, 12
	s_cselect_b32 s10, s11, s10
	s_or_b32 s11, s10, 64
	v_cmp_le_u32_e32 vcc, s11, v2
	v_cmp_le_u32_e64 s[98:99], s11, v0
	s_bcnt1_i32_b64 s20, vcc
	s_bcnt1_i32_b64 s21, s[98:99]
	s_add_i32 s21, s21, s20
	s_cmp_gt_u32 s21, 12
	s_cselect_b32 s10, s11, s10
	s_or_b32 s11, s10, 32
	v_cmp_le_u32_e32 vcc, s11, v2
	v_cmp_le_u32_e64 s[98:99], s11, v0
	s_bcnt1_i32_b64 s20, vcc
	s_bcnt1_i32_b64 s21, s[98:99]
	s_add_i32 s21, s21, s20
	s_cmp_gt_u32 s21, 12
	s_cselect_b32 s10, s11, s10
	s_or_b32 s11, s10, 16
	v_cmp_le_u32_e32 vcc, s11, v2
	v_cmp_le_u32_e64 s[98:99], s11, v0
	s_bcnt1_i32_b64 s20, vcc
	s_bcnt1_i32_b64 s21, s[98:99]
	s_add_i32 s21, s21, s20
	s_cmp_gt_u32 s21, 12
	s_cselect_b32 s10, s11, s10
	s_or_b32 s11, s10, 8
	v_cmp_le_u32_e32 vcc, s11, v2
	v_cmp_le_u32_e64 s[98:99], s11, v0
	s_bcnt1_i32_b64 s20, vcc
	s_bcnt1_i32_b64 s21, s[98:99]
	s_add_i32 s21, s21, s20
	s_cmp_gt_u32 s21, 12
	s_cselect_b32 s10, s11, s10
	s_or_b32 s11, s10, 4
	v_cmp_le_u32_e32 vcc, s11, v2
	v_cmp_le_u32_e64 s[98:99], s11, v0
	s_bcnt1_i32_b64 s20, vcc
	s_bcnt1_i32_b64 s21, s[98:99]
	s_add_i32 s21, s21, s20
	s_cmp_gt_u32 s21, 12
	s_cselect_b32 s10, s11, s10
	s_or_b32 s11, s10, 2
	v_cmp_le_u32_e32 vcc, s11, v2
	v_cmp_le_u32_e64 s[98:99], s11, v0
	s_bcnt1_i32_b64 s20, vcc
	s_bcnt1_i32_b64 s21, s[98:99]
	s_add_i32 s21, s21, s20
	s_cmp_gt_u32 s21, 12
	s_cselect_b32 s10, s11, s10
	s_or_b32 s11, s10, 1
	v_cmp_le_u32_e32 vcc, s11, v2
	v_cmp_le_u32_e64 s[98:99], s11, v0
	s_bcnt1_i32_b64 s20, vcc
	s_bcnt1_i32_b64 s21, s[98:99]
	s_add_i32 s21, s21, s20
	s_cmp_gt_u32 s21, 12
	s_cselect_b32 s10, s11, s10
	v_cmp_lt_u32_e64 s[78:79], s10, v2
	v_cmp_lt_u32_e64 s[84:85], s10, v0
	v_cmp_eq_u32_e64 s[36:37], s10, v2
	v_cmp_eq_u32_e64 s[20:21], s10, v0
	s_bcnt1_i32_b64 s10, s[78:79]
	s_bcnt1_i32_b64 s11, s[84:85]
	s_add_i32 s10, s11, s10
	s_cmp_gt_u32 s10, 12
	s_cselect_b64 s[52:53], -1, 0
	s_or_b64 s[62:63], s[20:21], s[36:37]
	s_cmp_eq_u64 s[62:63], 0
	s_cselect_b64 s[62:63], -1, 0
	s_or_b64 s[52:53], s[52:53], s[62:63]
	s_and_b64 vcc, exec, s[52:53]
	s_cbranch_vccnz .LBB0_164
	s_sub_i32 s58, 13, s10
	s_cmp_eq_u64 s[36:37], 0
	s_cbranch_scc0 .LBB0_161
	s_branch .LBB0_159
